# GEMM K-loops: MFMAs of each 16-cluster reordered so the two k-steps of an accumulator are adjacent (SrcC forwarded); bit-identical
# speedup vs baseline: 1.0078x; 1.0057x over previous
.LBB0_127:
	s_add_u32 s2, s0, 0xfff80080
	s_addc_u32 s3, s1, -1
	s_add_i32 s50, 0, 0x10000
	s_cmp_eq_u32 s49, 28
	s_cselect_b32 s5, s23, s3
	s_cselect_b32 s4, s27, s2
	s_cselect_b32 s3, s9, s48
	s_cselect_b32 s2, s46, s47
	s_add_i32 s52, 0, 0x14000
	v_add_u32_e32 v154, s50, v163
	v_add_u32_e32 v176, s52, v163
	ds_read_b128 v[142:145], v154
	ds_read_b128 v[146:149], v154 offset:1024
	ds_read_b128 v[150:153], v154 offset:2048
	ds_read_b128 v[154:157], v154 offset:3072
	ds_read_b128 v[158:161], v176
	ds_read_b128 v[168:171], v176 offset:1024
	ds_read_b128 v[172:175], v176 offset:2048
	ds_read_b128 v[176:179], v176 offset:3072
	v_lshl_add_u64 v[204:205], s[0:1], 0, v[138:139]
	s_add_i32 m0, s11, 0xc000
	ds_read_b128 v[180:183], v167
	ds_read_b128 v[184:187], v167 offset:1024
	ds_read_b128 v[188:191], v167 offset:2048
	ds_read_b128 v[192:195], v167 offset:3072
	ds_read_b128 v[196:199], v167 offset:4096
	ds_read_b128 v[200:203], v167 offset:5120
	ds_read_b128 v[210:213], v167 offset:6144
	ds_read_b128 v[214:217], v167 offset:7168
	global_load_lds_dwordx4 v[204:205], off
	v_lshl_add_u64 v[204:205], s[0:1], 0, v[140:141]
	s_add_i32 m0, s11, 0xe000
	s_nop 0
	global_load_lds_dwordx4 v[204:205], off
	s_waitcnt vmcnt(8)
	s_waitcnt lgkmcnt(0)
	s_barrier
	s_setprio 1
	s_waitcnt lgkmcnt(0)
	v_mfma_f32_16x16x32_bf16 v[126:129], v[142:145], v[180:183], v[126:129]
	v_mfma_f32_16x16x32_bf16 v[126:129], v[146:149], v[184:187], v[126:129]
	v_mfma_f32_16x16x32_bf16 v[122:125], v[150:153], v[180:183], v[122:125]
	v_mfma_f32_16x16x32_bf16 v[122:125], v[154:157], v[184:187], v[122:125]
	v_mfma_f32_16x16x32_bf16 v[110:113], v[142:145], v[188:191], v[110:113]
	v_mfma_f32_16x16x32_bf16 v[110:113], v[146:149], v[192:195], v[110:113]
	v_mfma_f32_16x16x32_bf16 v[106:109], v[150:153], v[188:191], v[106:109]
	v_mfma_f32_16x16x32_bf16 v[106:109], v[154:157], v[192:195], v[106:109]
	v_mfma_f32_16x16x32_bf16 v[94:97], v[142:145], v[196:199], v[94:97]
	v_mfma_f32_16x16x32_bf16 v[94:97], v[146:149], v[200:203], v[94:97]
	v_mfma_f32_16x16x32_bf16 v[90:93], v[150:153], v[196:199], v[90:93]
	v_mfma_f32_16x16x32_bf16 v[90:93], v[154:157], v[200:203], v[90:93]
	v_mfma_f32_16x16x32_bf16 v[78:81], v[142:145], v[210:213], v[78:81]
	v_mfma_f32_16x16x32_bf16 v[78:81], v[146:149], v[214:217], v[78:81]
	v_mfma_f32_16x16x32_bf16 v[74:77], v[150:153], v[210:213], v[74:77]
	v_mfma_f32_16x16x32_bf16 v[74:77], v[154:157], v[214:217], v[74:77]
	s_setprio 0
	s_setprio 1
	v_mfma_f32_16x16x32_bf16 v[118:121], v[158:161], v[180:183], v[118:121]
	v_mfma_f32_16x16x32_bf16 v[118:121], v[168:171], v[184:187], v[118:121]
	v_mfma_f32_16x16x32_bf16 v[114:117], v[172:175], v[180:183], v[114:117]
	v_mfma_f32_16x16x32_bf16 v[114:117], v[176:179], v[184:187], v[114:117]
	v_mfma_f32_16x16x32_bf16 v[102:105], v[158:161], v[188:191], v[102:105]
	v_mfma_f32_16x16x32_bf16 v[102:105], v[168:171], v[192:195], v[102:105]
	v_mfma_f32_16x16x32_bf16 v[98:101], v[172:175], v[188:191], v[98:101]
	v_mfma_f32_16x16x32_bf16 v[98:101], v[176:179], v[192:195], v[98:101]
	v_mfma_f32_16x16x32_bf16 v[86:89], v[158:161], v[196:199], v[86:89]
	v_mfma_f32_16x16x32_bf16 v[86:89], v[168:171], v[200:203], v[86:89]
	v_mfma_f32_16x16x32_bf16 v[82:85], v[172:175], v[196:199], v[82:85]
	v_mfma_f32_16x16x32_bf16 v[82:85], v[176:179], v[200:203], v[82:85]
	v_mfma_f32_16x16x32_bf16 v[70:73], v[158:161], v[210:213], v[70:73]
	v_mfma_f32_16x16x32_bf16 v[70:73], v[168:171], v[214:217], v[70:73]
	v_mfma_f32_16x16x32_bf16 v[66:69], v[172:175], v[210:213], v[66:69]
	v_mfma_f32_16x16x32_bf16 v[66:69], v[176:179], v[214:217], v[66:69]
	s_setprio 0
	s_barrier
	s_add_i32 s50, s50, s31
	v_lshl_add_u64 v[204:205], s[2:3], 0, v[0:1]
	s_mov_b32 m0, s50
	ds_read_b128 v[180:183], v167 offset:16384
	ds_read_b128 v[184:187], v167 offset:17408
	ds_read_b128 v[188:191], v167 offset:18432
	ds_read_b128 v[192:195], v167 offset:19456
	ds_read_b128 v[196:199], v167 offset:20480
	ds_read_b128 v[200:203], v167 offset:21504
	ds_read_b128 v[210:213], v167 offset:22528
	ds_read_b128 v[214:217], v167 offset:23552
	global_load_lds_dwordx4 v[204:205], off
	s_add_i32 m0, s50, 0x2000
	s_add_u32 s50, s2, 0x80000
	v_lshl_add_u64 v[206:207], s[2:3], 0, v[134:135]
	s_addc_u32 s51, s3, 0
	s_add_i32 s52, s52, s31
	global_load_lds_dwordx4 v[206:207], off
	v_lshl_add_u64 v[218:219], s[50:51], 0, v[0:1]
	s_mov_b32 m0, s52
	v_lshl_add_u64 v[220:221], s[4:5], 0, v[132:133]
	global_load_lds_dwordx4 v[218:219], off
	v_lshl_add_u64 v[218:219], s[50:51], 0, v[134:135]
	s_add_i32 m0, s52, 0x2000
	s_nop 0
	global_load_lds_dwordx4 v[218:219], off
	v_lshl_add_u64 v[218:219], s[4:5], 0, v[130:131]
	s_mov_b32 m0, s11
	s_nop 0
	global_load_lds_dwordx4 v[218:219], off
	s_mov_b32 m0, s35
	s_nop 0
	global_load_lds_dwordx4 v[220:221], off
	s_waitcnt vmcnt(8)
	s_waitcnt lgkmcnt(0)
	s_barrier
	s_setprio 1
	s_waitcnt lgkmcnt(0)
	v_mfma_f32_16x16x32_bf16 v[62:65], v[142:145], v[180:183], v[62:65]
	v_mfma_f32_16x16x32_bf16 v[62:65], v[146:149], v[184:187], v[62:65]
	v_mfma_f32_16x16x32_bf16 v[58:61], v[150:153], v[180:183], v[58:61]
	v_mfma_f32_16x16x32_bf16 v[58:61], v[154:157], v[184:187], v[58:61]
	v_mfma_f32_16x16x32_bf16 v[46:49], v[142:145], v[188:191], v[46:49]
	v_mfma_f32_16x16x32_bf16 v[46:49], v[146:149], v[192:195], v[46:49]
	v_mfma_f32_16x16x32_bf16 v[42:45], v[150:153], v[188:191], v[42:45]
	v_mfma_f32_16x16x32_bf16 v[42:45], v[154:157], v[192:195], v[42:45]
	v_mfma_f32_16x16x32_bf16 v[30:33], v[142:145], v[196:199], v[30:33]
	v_mfma_f32_16x16x32_bf16 v[30:33], v[146:149], v[200:203], v[30:33]
	v_mfma_f32_16x16x32_bf16 v[26:29], v[150:153], v[196:199], v[26:29]
	v_mfma_f32_16x16x32_bf16 v[26:29], v[154:157], v[200:203], v[26:29]
	v_mfma_f32_16x16x32_bf16 v[14:17], v[142:145], v[210:213], v[14:17]
	v_mfma_f32_16x16x32_bf16 v[14:17], v[146:149], v[214:217], v[14:17]
	v_mfma_f32_16x16x32_bf16 v[10:13], v[150:153], v[210:213], v[10:13]
	v_mfma_f32_16x16x32_bf16 v[10:13], v[154:157], v[214:217], v[10:13]
	s_setprio 0
	s_setprio 1
	v_mfma_f32_16x16x32_bf16 v[54:57], v[158:161], v[180:183], v[54:57]
	v_mfma_f32_16x16x32_bf16 v[54:57], v[168:171], v[184:187], v[54:57]
	v_mfma_f32_16x16x32_bf16 v[50:53], v[172:175], v[180:183], v[50:53]
	v_mfma_f32_16x16x32_bf16 v[50:53], v[176:179], v[184:187], v[50:53]
	v_mfma_f32_16x16x32_bf16 v[38:41], v[158:161], v[188:191], v[38:41]
	v_mfma_f32_16x16x32_bf16 v[38:41], v[168:171], v[192:195], v[38:41]
	v_mfma_f32_16x16x32_bf16 v[34:37], v[172:175], v[188:191], v[34:37]
	v_mfma_f32_16x16x32_bf16 v[34:37], v[176:179], v[192:195], v[34:37]
	v_mfma_f32_16x16x32_bf16 v[22:25], v[158:161], v[196:199], v[22:25]
	v_mfma_f32_16x16x32_bf16 v[22:25], v[168:171], v[200:203], v[22:25]
	v_mfma_f32_16x16x32_bf16 v[18:21], v[172:175], v[196:199], v[18:21]
	v_mfma_f32_16x16x32_bf16 v[18:21], v[176:179], v[200:203], v[18:21]
	v_mfma_f32_16x16x32_bf16 v[6:9], v[158:161], v[210:213], v[6:9]
	v_mfma_f32_16x16x32_bf16 v[6:9], v[168:171], v[214:217], v[6:9]
	v_mfma_f32_16x16x32_bf16 v[2:5], v[172:175], v[210:213], v[2:5]
	v_mfma_f32_16x16x32_bf16 v[2:5], v[176:179], v[214:217], v[2:5]
	s_setprio 0
	s_barrier
	s_add_i32 s50, 0, 0x18000
	s_add_i32 s51, 0, 0x1c000
	v_add_u32_e32 v154, s50, v163
	v_add_u32_e32 v176, s51, v163
	ds_read_b128 v[142:145], v154
	ds_read_b128 v[146:149], v154 offset:1024
	ds_read_b128 v[150:153], v154 offset:2048
	ds_read_b128 v[154:157], v154 offset:3072
	ds_read_b128 v[158:161], v176
	ds_read_b128 v[168:171], v176 offset:1024
	ds_read_b128 v[172:175], v176 offset:2048
	ds_read_b128 v[176:179], v176 offset:3072
	s_add_u32 s4, s4, 0x80000
	s_addc_u32 s5, s5, 0
	s_mov_b32 m0, s36
	v_lshl_add_u64 v[222:223], s[4:5], 0, v[130:131]
	ds_read_b128 v[180:183], v167 offset:32768
	ds_read_b128 v[184:187], v167 offset:33792
	ds_read_b128 v[188:191], v167 offset:34816
	ds_read_b128 v[192:195], v167 offset:35840
	ds_read_b128 v[196:199], v167 offset:36864
	ds_read_b128 v[200:203], v167 offset:37888
	ds_read_b128 v[210:213], v167 offset:38912
	ds_read_b128 v[214:217], v167 offset:39936
	global_load_lds_dwordx4 v[222:223], off
	v_lshl_add_u64 v[222:223], s[4:5], 0, v[132:133]
	s_mov_b32 m0, s37
	s_nop 0
	global_load_lds_dwordx4 v[222:223], off
	s_waitcnt vmcnt(8)
	s_waitcnt lgkmcnt(0)
	s_barrier
	s_setprio 1
	s_waitcnt lgkmcnt(0)
	v_mfma_f32_16x16x32_bf16 v[126:129], v[142:145], v[180:183], v[126:129]
	v_mfma_f32_16x16x32_bf16 v[126:129], v[146:149], v[184:187], v[126:129]
	v_mfma_f32_16x16x32_bf16 v[122:125], v[150:153], v[180:183], v[122:125]
	v_mfma_f32_16x16x32_bf16 v[122:125], v[154:157], v[184:187], v[122:125]
	v_mfma_f32_16x16x32_bf16 v[110:113], v[142:145], v[188:191], v[110:113]
	v_mfma_f32_16x16x32_bf16 v[110:113], v[146:149], v[192:195], v[110:113]
	v_mfma_f32_16x16x32_bf16 v[106:109], v[150:153], v[188:191], v[106:109]
	v_mfma_f32_16x16x32_bf16 v[106:109], v[154:157], v[192:195], v[106:109]
	v_mfma_f32_16x16x32_bf16 v[94:97], v[142:145], v[196:199], v[94:97]
	v_mfma_f32_16x16x32_bf16 v[94:97], v[146:149], v[200:203], v[94:97]
	v_mfma_f32_16x16x32_bf16 v[90:93], v[150:153], v[196:199], v[90:93]
	v_mfma_f32_16x16x32_bf16 v[90:93], v[154:157], v[200:203], v[90:93]
	v_mfma_f32_16x16x32_bf16 v[78:81], v[142:145], v[210:213], v[78:81]
	v_mfma_f32_16x16x32_bf16 v[78:81], v[146:149], v[214:217], v[78:81]
	v_mfma_f32_16x16x32_bf16 v[74:77], v[150:153], v[210:213], v[74:77]
	v_mfma_f32_16x16x32_bf16 v[74:77], v[154:157], v[214:217], v[74:77]
	s_setprio 0
	s_setprio 1
	v_mfma_f32_16x16x32_bf16 v[118:121], v[158:161], v[180:183], v[118:121]
	v_mfma_f32_16x16x32_bf16 v[118:121], v[168:171], v[184:187], v[118:121]
	v_mfma_f32_16x16x32_bf16 v[114:117], v[172:175], v[180:183], v[114:117]
	v_mfma_f32_16x16x32_bf16 v[114:117], v[176:179], v[184:187], v[114:117]
	v_mfma_f32_16x16x32_bf16 v[102:105], v[158:161], v[188:191], v[102:105]
	v_mfma_f32_16x16x32_bf16 v[102:105], v[168:171], v[192:195], v[102:105]
	v_mfma_f32_16x16x32_bf16 v[98:101], v[172:175], v[188:191], v[98:101]
	v_mfma_f32_16x16x32_bf16 v[98:101], v[176:179], v[192:195], v[98:101]
	v_mfma_f32_16x16x32_bf16 v[86:89], v[158:161], v[196:199], v[86:89]
	v_mfma_f32_16x16x32_bf16 v[86:89], v[168:171], v[200:203], v[86:89]
	v_mfma_f32_16x16x32_bf16 v[82:85], v[172:175], v[196:199], v[82:85]
	v_mfma_f32_16x16x32_bf16 v[82:85], v[176:179], v[200:203], v[82:85]
	v_mfma_f32_16x16x32_bf16 v[70:73], v[158:161], v[210:213], v[70:73]
	v_mfma_f32_16x16x32_bf16 v[70:73], v[168:171], v[214:217], v[70:73]
	v_mfma_f32_16x16x32_bf16 v[66:69], v[172:175], v[210:213], v[66:69]
	v_mfma_f32_16x16x32_bf16 v[66:69], v[176:179], v[214:217], v[66:69]
	s_setprio 0
	s_barrier
	s_add_i32 s4, s50, s31
	v_lshl_add_u64 v[204:205], v[204:205], 0, s[68:69]
	s_mov_b32 m0, s4
	ds_read_b128 v[180:183], v167 offset:49152
	ds_read_b128 v[184:187], v167 offset:50176
	ds_read_b128 v[188:191], v167 offset:51200
	ds_read_b128 v[192:195], v167 offset:52224
	ds_read_b128 v[196:199], v167 offset:53248
	ds_read_b128 v[200:203], v167 offset:54272
	ds_read_b128 v[210:213], v167 offset:55296
	ds_read_b128 v[214:217], v167 offset:56320
	global_load_lds_dwordx4 v[204:205], off
	s_add_i32 m0, s4, 0x2000
	s_add_u32 s2, s2, 0x80080
	v_lshl_add_u64 v[204:205], v[206:207], 0, s[68:69]
	s_addc_u32 s3, s3, 0
	s_add_i32 s4, s51, s31
	global_load_lds_dwordx4 v[204:205], off
	v_lshl_add_u64 v[204:205], s[2:3], 0, v[0:1]
	s_mov_b32 m0, s4
	s_nop 0
	global_load_lds_dwordx4 v[204:205], off
	v_lshl_add_u64 v[204:205], s[2:3], 0, v[134:135]
	s_add_i32 m0, s4, 0x2000
	s_nop 0
	global_load_lds_dwordx4 v[204:205], off
	v_lshl_add_u64 v[204:205], v[218:219], 0, s[68:69]
	s_mov_b32 m0, s38
	s_nop 0
	global_load_lds_dwordx4 v[204:205], off
	v_lshl_add_u64 v[204:205], v[220:221], 0, s[68:69]
	s_mov_b32 m0, s39
	s_nop 0
	global_load_lds_dwordx4 v[204:205], off
	s_waitcnt vmcnt(8)
	s_waitcnt lgkmcnt(0)
	s_barrier
	s_setprio 1
	s_waitcnt lgkmcnt(0)
	v_mfma_f32_16x16x32_bf16 v[62:65], v[142:145], v[180:183], v[62:65]
	v_mfma_f32_16x16x32_bf16 v[62:65], v[146:149], v[184:187], v[62:65]
	v_mfma_f32_16x16x32_bf16 v[58:61], v[150:153], v[180:183], v[58:61]
	v_mfma_f32_16x16x32_bf16 v[58:61], v[154:157], v[184:187], v[58:61]
	v_mfma_f32_16x16x32_bf16 v[46:49], v[142:145], v[188:191], v[46:49]
	v_mfma_f32_16x16x32_bf16 v[46:49], v[146:149], v[192:195], v[46:49]
	v_mfma_f32_16x16x32_bf16 v[42:45], v[150:153], v[188:191], v[42:45]
	v_mfma_f32_16x16x32_bf16 v[42:45], v[154:157], v[192:195], v[42:45]
	v_mfma_f32_16x16x32_bf16 v[30:33], v[142:145], v[196:199], v[30:33]
	v_mfma_f32_16x16x32_bf16 v[30:33], v[146:149], v[200:203], v[30:33]
	v_mfma_f32_16x16x32_bf16 v[26:29], v[150:153], v[196:199], v[26:29]
	v_mfma_f32_16x16x32_bf16 v[26:29], v[154:157], v[200:203], v[26:29]
	v_mfma_f32_16x16x32_bf16 v[14:17], v[142:145], v[210:213], v[14:17]
	v_mfma_f32_16x16x32_bf16 v[14:17], v[146:149], v[214:217], v[14:17]
	v_mfma_f32_16x16x32_bf16 v[10:13], v[150:153], v[210:213], v[10:13]
	v_mfma_f32_16x16x32_bf16 v[10:13], v[154:157], v[214:217], v[10:13]
	s_setprio 0
	s_setprio 1
	v_mfma_f32_16x16x32_bf16 v[54:57], v[158:161], v[180:183], v[54:57]
	v_mfma_f32_16x16x32_bf16 v[54:57], v[168:171], v[184:187], v[54:57]
	v_mfma_f32_16x16x32_bf16 v[50:53], v[172:175], v[180:183], v[50:53]
	v_mfma_f32_16x16x32_bf16 v[50:53], v[176:179], v[184:187], v[50:53]
	v_mfma_f32_16x16x32_bf16 v[38:41], v[158:161], v[188:191], v[38:41]
	v_mfma_f32_16x16x32_bf16 v[38:41], v[168:171], v[192:195], v[38:41]
	v_mfma_f32_16x16x32_bf16 v[34:37], v[172:175], v[188:191], v[34:37]
	v_mfma_f32_16x16x32_bf16 v[34:37], v[176:179], v[192:195], v[34:37]
	v_mfma_f32_16x16x32_bf16 v[22:25], v[158:161], v[196:199], v[22:25]
	v_mfma_f32_16x16x32_bf16 v[22:25], v[168:171], v[200:203], v[22:25]
	v_mfma_f32_16x16x32_bf16 v[18:21], v[172:175], v[196:199], v[18:21]
	v_mfma_f32_16x16x32_bf16 v[18:21], v[176:179], v[200:203], v[18:21]
	v_mfma_f32_16x16x32_bf16 v[6:9], v[158:161], v[210:213], v[6:9]
	v_mfma_f32_16x16x32_bf16 v[6:9], v[168:171], v[214:217], v[6:9]
	v_mfma_f32_16x16x32_bf16 v[2:5], v[172:175], v[210:213], v[2:5]
	v_mfma_f32_16x16x32_bf16 v[2:5], v[176:179], v[214:217], v[2:5]
	s_setprio 0
	s_barrier
	s_add_i32 s49, s49, 2
	s_add_u32 s0, s0, 0x100
	s_addc_u32 s1, s1, 0
	s_add_u32 s47, s47, 0x100
	s_addc_u32 s48, s48, 0
	s_cmp_gt_u32 s49, 29
	s_cbranch_scc0 .LBB0_127
	s_and_b64 vcc, exec, s[18:19]
	s_cbranch_vccz .LBB0_130
	s_barrier

.LBB0_376:
	s_add_u32 s10, s22, s8
	s_addc_u32 s11, s23, s9
	s_add_u32 s10, s10, 0x14100100
	s_addc_u32 s11, s11, 0
	s_add_u32 s27, s24, s8
	s_addc_u32 s28, s25, s9
	s_cmpk_eq_i32 s8, 0xf00
	s_cselect_b32 s13, s7, s11
	s_cselect_b32 s12, s6, s10
	s_cselect_b32 s11, s3, s28
	s_cselect_b32 s10, s2, s27
	s_add_i32 s27, 0, 0x14000
	v_add_u32_e32 v143, s27, v141
	s_add_i32 s28, 0, 0x10000
	ds_read_b128 v[144:147], v143 offset:3072
	ds_read_b128 v[148:151], v143 offset:2048
	ds_read_b128 v[152:155], v143 offset:1024
	ds_read_b128 v[156:159], v143
	v_add_u32_e32 v143, s28, v141
	ds_read_b128 v[160:163], v143 offset:3072
	ds_read_b128 v[164:167], v143 offset:2048
	ds_read_b128 v[168:171], v143 offset:1024
	ds_read_b128 v[174:177], v143
	v_lshl_add_u64 v[206:207], v[136:137], 0, s[8:9]
	s_add_i32 m0, s19, 0xc000
	ds_read_b128 v[178:181], v142
	ds_read_b128 v[182:185], v142 offset:1024
	ds_read_b128 v[186:189], v142 offset:2048
	ds_read_b128 v[190:193], v142 offset:3072
	ds_read_b128 v[194:197], v142 offset:4096
	ds_read_b128 v[198:201], v142 offset:5120
	ds_read_b128 v[202:205], v142 offset:6144
	ds_read_b128 v[210:213], v142 offset:7168
	global_load_lds_dwordx4 v[206:207], off
	v_lshl_add_u64 v[206:207], v[138:139], 0, s[8:9]
	s_add_i32 m0, s19, 0xe000
	s_nop 0
	global_load_lds_dwordx4 v[206:207], off
	s_waitcnt vmcnt(8)
	s_waitcnt lgkmcnt(0)
	s_barrier
	s_setprio 1
	s_waitcnt lgkmcnt(0)
	v_mfma_f32_16x16x32_bf16 v[126:129], v[174:177], v[178:181], v[126:129]
	v_mfma_f32_16x16x32_bf16 v[126:129], v[168:171], v[182:185], v[126:129]
	v_mfma_f32_16x16x32_bf16 v[122:125], v[164:167], v[178:181], v[122:125]
	v_mfma_f32_16x16x32_bf16 v[122:125], v[160:163], v[182:185], v[122:125]
	v_mfma_f32_16x16x32_bf16 v[110:113], v[174:177], v[186:189], v[110:113]
	v_mfma_f32_16x16x32_bf16 v[110:113], v[168:171], v[190:193], v[110:113]
	v_mfma_f32_16x16x32_bf16 v[106:109], v[164:167], v[186:189], v[106:109]
	v_mfma_f32_16x16x32_bf16 v[106:109], v[160:163], v[190:193], v[106:109]
	v_mfma_f32_16x16x32_bf16 v[94:97], v[174:177], v[194:197], v[94:97]
	v_mfma_f32_16x16x32_bf16 v[94:97], v[168:171], v[198:201], v[94:97]
	v_mfma_f32_16x16x32_bf16 v[90:93], v[164:167], v[194:197], v[90:93]
	v_mfma_f32_16x16x32_bf16 v[90:93], v[160:163], v[198:201], v[90:93]
	v_mfma_f32_16x16x32_bf16 v[78:81], v[174:177], v[202:205], v[78:81]
	v_mfma_f32_16x16x32_bf16 v[78:81], v[168:171], v[210:213], v[78:81]
	v_mfma_f32_16x16x32_bf16 v[74:77], v[164:167], v[202:205], v[74:77]
	v_mfma_f32_16x16x32_bf16 v[74:77], v[160:163], v[210:213], v[74:77]
	s_setprio 0
	s_setprio 1
	v_mfma_f32_16x16x32_bf16 v[118:121], v[156:159], v[178:181], v[118:121]
	v_mfma_f32_16x16x32_bf16 v[118:121], v[152:155], v[182:185], v[118:121]
	v_mfma_f32_16x16x32_bf16 v[114:117], v[148:151], v[178:181], v[114:117]
	v_mfma_f32_16x16x32_bf16 v[114:117], v[144:147], v[182:185], v[114:117]
	v_mfma_f32_16x16x32_bf16 v[102:105], v[156:159], v[186:189], v[102:105]
	v_mfma_f32_16x16x32_bf16 v[102:105], v[152:155], v[190:193], v[102:105]
	v_mfma_f32_16x16x32_bf16 v[98:101], v[148:151], v[186:189], v[98:101]
	v_mfma_f32_16x16x32_bf16 v[98:101], v[144:147], v[190:193], v[98:101]
	v_mfma_f32_16x16x32_bf16 v[86:89], v[156:159], v[194:197], v[86:89]
	v_mfma_f32_16x16x32_bf16 v[86:89], v[152:155], v[198:201], v[86:89]
	v_mfma_f32_16x16x32_bf16 v[82:85], v[148:151], v[194:197], v[82:85]
	v_mfma_f32_16x16x32_bf16 v[82:85], v[144:147], v[198:201], v[82:85]
	v_mfma_f32_16x16x32_bf16 v[70:73], v[156:159], v[202:205], v[70:73]
	v_mfma_f32_16x16x32_bf16 v[70:73], v[152:155], v[210:213], v[70:73]
	v_mfma_f32_16x16x32_bf16 v[66:69], v[148:151], v[202:205], v[66:69]
	v_mfma_f32_16x16x32_bf16 v[66:69], v[144:147], v[210:213], v[66:69]
	s_setprio 0
	s_barrier
	s_add_i32 s28, s28, s18
	v_lshl_add_u64 v[206:207], s[10:11], 0, v[0:1]
	s_mov_b32 m0, s28
	ds_read_b128 v[178:181], v142 offset:16384
	ds_read_b128 v[182:185], v142 offset:17408
	ds_read_b128 v[186:189], v142 offset:18432
	ds_read_b128 v[190:193], v142 offset:19456
	ds_read_b128 v[194:197], v142 offset:20480
	ds_read_b128 v[198:201], v142 offset:21504
	ds_read_b128 v[202:205], v142 offset:22528
	ds_read_b128 v[210:213], v142 offset:23552
	global_load_lds_dwordx4 v[206:207], off
	s_add_i32 m0, s28, 0x2000
	s_add_u32 s28, s10, 0x80000
	v_lshl_add_u64 v[214:215], s[10:11], 0, v[130:131]
	s_addc_u32 s29, s11, 0
	s_add_i32 s27, s27, s18
	global_load_lds_dwordx4 v[214:215], off
	v_lshl_add_u64 v[216:217], s[28:29], 0, v[0:1]
	s_mov_b32 m0, s27
	v_lshl_add_u64 v[218:219], s[12:13], 0, v[134:135]
	global_load_lds_dwordx4 v[216:217], off
	v_lshl_add_u64 v[216:217], s[28:29], 0, v[130:131]
	s_add_i32 m0, s27, 0x2000
	s_nop 0
	global_load_lds_dwordx4 v[216:217], off
	v_lshl_add_u64 v[216:217], s[12:13], 0, v[132:133]
	s_mov_b32 m0, s19
	s_nop 0
	global_load_lds_dwordx4 v[216:217], off
	s_mov_b32 m0, s1
	s_nop 0
	global_load_lds_dwordx4 v[218:219], off
	s_waitcnt vmcnt(8)
	s_waitcnt lgkmcnt(0)
	s_barrier
	s_setprio 1
	s_waitcnt lgkmcnt(0)
	v_mfma_f32_16x16x32_bf16 v[62:65], v[174:177], v[178:181], v[62:65]
	v_mfma_f32_16x16x32_bf16 v[62:65], v[168:171], v[182:185], v[62:65]
	v_mfma_f32_16x16x32_bf16 v[58:61], v[164:167], v[178:181], v[58:61]
	v_mfma_f32_16x16x32_bf16 v[58:61], v[160:163], v[182:185], v[58:61]
	v_mfma_f32_16x16x32_bf16 v[46:49], v[174:177], v[186:189], v[46:49]
	v_mfma_f32_16x16x32_bf16 v[46:49], v[168:171], v[190:193], v[46:49]
	v_mfma_f32_16x16x32_bf16 v[42:45], v[164:167], v[186:189], v[42:45]
	v_mfma_f32_16x16x32_bf16 v[42:45], v[160:163], v[190:193], v[42:45]
	v_mfma_f32_16x16x32_bf16 v[30:33], v[174:177], v[194:197], v[30:33]
	v_mfma_f32_16x16x32_bf16 v[30:33], v[168:171], v[198:201], v[30:33]
	v_mfma_f32_16x16x32_bf16 v[26:29], v[164:167], v[194:197], v[26:29]
	v_mfma_f32_16x16x32_bf16 v[26:29], v[160:163], v[198:201], v[26:29]
	v_mfma_f32_16x16x32_bf16 v[14:17], v[174:177], v[202:205], v[14:17]
	v_mfma_f32_16x16x32_bf16 v[14:17], v[168:171], v[210:213], v[14:17]
	v_mfma_f32_16x16x32_bf16 v[10:13], v[164:167], v[202:205], v[10:13]
	v_mfma_f32_16x16x32_bf16 v[10:13], v[160:163], v[210:213], v[10:13]
	s_setprio 0
	s_setprio 1
	v_mfma_f32_16x16x32_bf16 v[54:57], v[156:159], v[178:181], v[54:57]
	v_mfma_f32_16x16x32_bf16 v[54:57], v[152:155], v[182:185], v[54:57]
	v_mfma_f32_16x16x32_bf16 v[50:53], v[148:151], v[178:181], v[50:53]
	v_mfma_f32_16x16x32_bf16 v[50:53], v[144:147], v[182:185], v[50:53]
	v_mfma_f32_16x16x32_bf16 v[38:41], v[156:159], v[186:189], v[38:41]
	v_mfma_f32_16x16x32_bf16 v[38:41], v[152:155], v[190:193], v[38:41]
	v_mfma_f32_16x16x32_bf16 v[34:37], v[148:151], v[186:189], v[34:37]
	v_mfma_f32_16x16x32_bf16 v[34:37], v[144:147], v[190:193], v[34:37]
	v_mfma_f32_16x16x32_bf16 v[22:25], v[156:159], v[194:197], v[22:25]
	v_mfma_f32_16x16x32_bf16 v[22:25], v[152:155], v[198:201], v[22:25]
	v_mfma_f32_16x16x32_bf16 v[18:21], v[148:151], v[194:197], v[18:21]
	v_mfma_f32_16x16x32_bf16 v[18:21], v[144:147], v[198:201], v[18:21]
	v_mfma_f32_16x16x32_bf16 v[6:9], v[156:159], v[202:205], v[6:9]
	v_mfma_f32_16x16x32_bf16 v[6:9], v[152:155], v[210:213], v[6:9]
	v_mfma_f32_16x16x32_bf16 v[2:5], v[148:151], v[202:205], v[2:5]
	v_mfma_f32_16x16x32_bf16 v[2:5], v[144:147], v[210:213], v[2:5]
	s_setprio 0
	s_barrier
	s_add_i32 s27, 0, 0x18000
	v_add_u32_e32 v143, s27, v141
	s_add_i32 s28, 0, 0x1c000
	ds_read_b128 v[144:147], v143
	ds_read_b128 v[148:151], v143 offset:1024
	ds_read_b128 v[152:155], v143 offset:2048
	ds_read_b128 v[156:159], v143 offset:3072
	v_add_u32_e32 v143, s28, v141
	ds_read_b128 v[160:163], v143
	ds_read_b128 v[164:167], v143 offset:1024
	ds_read_b128 v[168:171], v143 offset:2048
	ds_read_b128 v[174:177], v143 offset:3072
	s_add_u32 s12, s12, 0x80000
	s_addc_u32 s13, s13, 0
	s_mov_b32 m0, s14
	v_lshl_add_u64 v[220:221], s[12:13], 0, v[132:133]
	ds_read_b128 v[178:181], v142 offset:32768
	ds_read_b128 v[182:185], v142 offset:33792
	ds_read_b128 v[186:189], v142 offset:34816
	ds_read_b128 v[190:193], v142 offset:35840
	ds_read_b128 v[194:197], v142 offset:36864
	ds_read_b128 v[198:201], v142 offset:37888
	ds_read_b128 v[202:205], v142 offset:38912
	ds_read_b128 v[210:213], v142 offset:39936
	global_load_lds_dwordx4 v[220:221], off
	v_lshl_add_u64 v[220:221], s[12:13], 0, v[134:135]
	s_mov_b32 m0, s15
	s_nop 0
	global_load_lds_dwordx4 v[220:221], off
	s_waitcnt vmcnt(8)
	s_waitcnt lgkmcnt(0)
	s_barrier
	s_setprio 1
	s_waitcnt lgkmcnt(0)
	v_mfma_f32_16x16x32_bf16 v[126:129], v[144:147], v[178:181], v[126:129]
	v_mfma_f32_16x16x32_bf16 v[126:129], v[148:151], v[182:185], v[126:129]
	v_mfma_f32_16x16x32_bf16 v[122:125], v[152:155], v[178:181], v[122:125]
	v_mfma_f32_16x16x32_bf16 v[122:125], v[156:159], v[182:185], v[122:125]
	v_mfma_f32_16x16x32_bf16 v[110:113], v[144:147], v[186:189], v[110:113]
	v_mfma_f32_16x16x32_bf16 v[110:113], v[148:151], v[190:193], v[110:113]
	v_mfma_f32_16x16x32_bf16 v[106:109], v[152:155], v[186:189], v[106:109]
	v_mfma_f32_16x16x32_bf16 v[106:109], v[156:159], v[190:193], v[106:109]
	v_mfma_f32_16x16x32_bf16 v[94:97], v[144:147], v[194:197], v[94:97]
	v_mfma_f32_16x16x32_bf16 v[94:97], v[148:151], v[198:201], v[94:97]
	v_mfma_f32_16x16x32_bf16 v[90:93], v[152:155], v[194:197], v[90:93]
	v_mfma_f32_16x16x32_bf16 v[90:93], v[156:159], v[198:201], v[90:93]
	v_mfma_f32_16x16x32_bf16 v[78:81], v[144:147], v[202:205], v[78:81]
	v_mfma_f32_16x16x32_bf16 v[78:81], v[148:151], v[210:213], v[78:81]
	v_mfma_f32_16x16x32_bf16 v[74:77], v[152:155], v[202:205], v[74:77]
	v_mfma_f32_16x16x32_bf16 v[74:77], v[156:159], v[210:213], v[74:77]
	s_setprio 0
	s_setprio 1
	v_mfma_f32_16x16x32_bf16 v[118:121], v[160:163], v[178:181], v[118:121]
	v_mfma_f32_16x16x32_bf16 v[118:121], v[164:167], v[182:185], v[118:121]
	v_mfma_f32_16x16x32_bf16 v[114:117], v[168:171], v[178:181], v[114:117]
	v_mfma_f32_16x16x32_bf16 v[114:117], v[174:177], v[182:185], v[114:117]
	v_mfma_f32_16x16x32_bf16 v[102:105], v[160:163], v[186:189], v[102:105]
	v_mfma_f32_16x16x32_bf16 v[102:105], v[164:167], v[190:193], v[102:105]
	v_mfma_f32_16x16x32_bf16 v[98:101], v[168:171], v[186:189], v[98:101]
	v_mfma_f32_16x16x32_bf16 v[98:101], v[174:177], v[190:193], v[98:101]
	v_mfma_f32_16x16x32_bf16 v[86:89], v[160:163], v[194:197], v[86:89]
	v_mfma_f32_16x16x32_bf16 v[86:89], v[164:167], v[198:201], v[86:89]
	v_mfma_f32_16x16x32_bf16 v[82:85], v[168:171], v[194:197], v[82:85]
	v_mfma_f32_16x16x32_bf16 v[82:85], v[174:177], v[198:201], v[82:85]
	v_mfma_f32_16x16x32_bf16 v[70:73], v[160:163], v[202:205], v[70:73]
	v_mfma_f32_16x16x32_bf16 v[70:73], v[164:167], v[210:213], v[70:73]
	v_mfma_f32_16x16x32_bf16 v[66:69], v[168:171], v[202:205], v[66:69]
	v_mfma_f32_16x16x32_bf16 v[66:69], v[174:177], v[210:213], v[66:69]
	s_setprio 0
	s_barrier
	s_add_i32 s12, s27, s18
	v_lshl_add_u64 v[206:207], v[206:207], 0, s[68:69]
	s_mov_b32 m0, s12
	ds_read_b128 v[178:181], v142 offset:49152
	ds_read_b128 v[182:185], v142 offset:50176
	ds_read_b128 v[186:189], v142 offset:51200
	ds_read_b128 v[190:193], v142 offset:52224
	ds_read_b128 v[194:197], v142 offset:53248
	ds_read_b128 v[198:201], v142 offset:54272
	ds_read_b128 v[202:205], v142 offset:55296
	ds_read_b128 v[210:213], v142 offset:56320
	global_load_lds_dwordx4 v[206:207], off
	s_add_i32 m0, s12, 0x2000
	s_add_u32 s10, s10, 0x80080
	v_lshl_add_u64 v[206:207], v[214:215], 0, s[68:69]
	s_addc_u32 s11, s11, 0
	s_add_i32 s12, s28, s18
	global_load_lds_dwordx4 v[206:207], off
	v_lshl_add_u64 v[206:207], s[10:11], 0, v[0:1]
	s_mov_b32 m0, s12
	s_nop 0
	global_load_lds_dwordx4 v[206:207], off
	v_lshl_add_u64 v[206:207], s[10:11], 0, v[130:131]
	s_add_i32 m0, s12, 0x2000
	s_nop 0
	global_load_lds_dwordx4 v[206:207], off
	v_lshl_add_u64 v[206:207], v[216:217], 0, s[68:69]
	s_mov_b32 m0, s20
	s_nop 0
	global_load_lds_dwordx4 v[206:207], off
	v_lshl_add_u64 v[206:207], v[218:219], 0, s[68:69]
	s_mov_b32 m0, s21
	s_nop 0
	global_load_lds_dwordx4 v[206:207], off
	s_waitcnt vmcnt(8)
	s_waitcnt lgkmcnt(0)
	s_barrier
	s_setprio 1
	s_waitcnt lgkmcnt(0)
	v_mfma_f32_16x16x32_bf16 v[62:65], v[144:147], v[178:181], v[62:65]
	v_mfma_f32_16x16x32_bf16 v[62:65], v[148:151], v[182:185], v[62:65]
	v_mfma_f32_16x16x32_bf16 v[58:61], v[152:155], v[178:181], v[58:61]
	v_mfma_f32_16x16x32_bf16 v[58:61], v[156:159], v[182:185], v[58:61]
	v_mfma_f32_16x16x32_bf16 v[46:49], v[144:147], v[186:189], v[46:49]
	v_mfma_f32_16x16x32_bf16 v[46:49], v[148:151], v[190:193], v[46:49]
	v_mfma_f32_16x16x32_bf16 v[42:45], v[152:155], v[186:189], v[42:45]
	v_mfma_f32_16x16x32_bf16 v[42:45], v[156:159], v[190:193], v[42:45]
	v_mfma_f32_16x16x32_bf16 v[30:33], v[144:147], v[194:197], v[30:33]
	v_mfma_f32_16x16x32_bf16 v[30:33], v[148:151], v[198:201], v[30:33]
	v_mfma_f32_16x16x32_bf16 v[26:29], v[152:155], v[194:197], v[26:29]
	v_mfma_f32_16x16x32_bf16 v[26:29], v[156:159], v[198:201], v[26:29]
	v_mfma_f32_16x16x32_bf16 v[14:17], v[144:147], v[202:205], v[14:17]
	v_mfma_f32_16x16x32_bf16 v[14:17], v[148:151], v[210:213], v[14:17]
	v_mfma_f32_16x16x32_bf16 v[10:13], v[152:155], v[202:205], v[10:13]
	v_mfma_f32_16x16x32_bf16 v[10:13], v[156:159], v[210:213], v[10:13]
	s_setprio 0
	s_setprio 1
	v_mfma_f32_16x16x32_bf16 v[54:57], v[160:163], v[178:181], v[54:57]
	v_mfma_f32_16x16x32_bf16 v[54:57], v[164:167], v[182:185], v[54:57]
	v_mfma_f32_16x16x32_bf16 v[50:53], v[168:171], v[178:181], v[50:53]
	v_mfma_f32_16x16x32_bf16 v[50:53], v[174:177], v[182:185], v[50:53]
	v_mfma_f32_16x16x32_bf16 v[38:41], v[160:163], v[186:189], v[38:41]
	v_mfma_f32_16x16x32_bf16 v[38:41], v[164:167], v[190:193], v[38:41]
	v_mfma_f32_16x16x32_bf16 v[34:37], v[168:171], v[186:189], v[34:37]
	v_mfma_f32_16x16x32_bf16 v[34:37], v[174:177], v[190:193], v[34:37]
	v_mfma_f32_16x16x32_bf16 v[22:25], v[160:163], v[194:197], v[22:25]
	v_mfma_f32_16x16x32_bf16 v[22:25], v[164:167], v[198:201], v[22:25]
	v_mfma_f32_16x16x32_bf16 v[18:21], v[168:171], v[194:197], v[18:21]
	v_mfma_f32_16x16x32_bf16 v[18:21], v[174:177], v[198:201], v[18:21]
	v_mfma_f32_16x16x32_bf16 v[6:9], v[160:163], v[202:205], v[6:9]
	v_mfma_f32_16x16x32_bf16 v[6:9], v[164:167], v[210:213], v[6:9]
	v_mfma_f32_16x16x32_bf16 v[2:5], v[168:171], v[202:205], v[2:5]
	v_mfma_f32_16x16x32_bf16 v[2:5], v[174:177], v[210:213], v[2:5]
	s_setprio 0
	s_barrier
	s_add_i32 s26, s26, 2
	s_add_u32 s8, s8, 0x100
	s_addc_u32 s9, s9, 0
	s_cmp_gt_u32 s26, 29
	s_cbranch_scc0 .LBB0_376
	s_cmpk_lt_u32 s17, 0x100
	s_cbranch_scc0 .LBB0_379
	s_barrier
